# SP2 super-phase K loops in P1,P7,P13,P14 + top-of-unit bias loads in P1,P7
# baseline (speedup 1.0000x reference)
.LBB0_184:
	s_add_u32 s28, s12, 0x4e00000
	s_addc_u32 s29, s13, 0
	s_add_u32 s33, s12, 0x2100000
	s_addc_u32 s35, s13, 0
	s_sext_i32_i8 s20, s8
	s_lshl_b32 s8, s8, 9
	s_and_b32 s8, s8, 0x600
	s_add_u32 s10, s28, s10
	s_addc_u32 s11, s29, s11
	s_add_u32 s60, s10, s8
	s_addc_u32 s61, s11, 0
	s_lshl_b32 s10, s20, 8
	s_ashr_i32 s11, s10, 31
	s_lshl_b64 s[10:11], s[10:11], 2
	s_add_u32 s58, s33, s10
	s_mov_b64 s[38:39], 0x80
	s_addc_u32 s59, s35, s11
	v_lshl_add_u64 v[10:11], v[2:3], 0, s[38:39]
	s_add_i32 m0, s7, 0x18000
	s_mov_b64 s[42:43], 0x20080
	s_waitcnt vmcnt(2)
	s_barrier
	global_load_lds_dwordx4 v[10:11], off
	v_lshl_add_u64 v[10:11], v[2:3], 0, s[42:43]
	s_add_i32 m0, s7, 0x1a000
	s_add_i32 s37, s7, 0x8000
	global_load_lds_dwordx4 v[10:11], off
	v_lshl_add_u64 v[10:11], v[4:5], 0, s[38:39]
	s_mov_b32 m0, s37
	s_add_i32 s40, s7, 0xa000
	global_load_lds_dwordx4 v[10:11], off
	v_lshl_add_u64 v[4:5], v[4:5], 0, s[42:43]
	s_mov_b32 m0, s40
	s_mov_b64 s[44:45], 0x40080
	global_load_lds_dwordx4 v[4:5], off
	v_lshl_add_u64 v[4:5], v[2:3], 0, s[44:45]
	s_add_i32 m0, s7, 0x1c000
	s_mov_b64 s[46:47], 0x60080
	global_load_lds_dwordx4 v[4:5], off
	v_lshl_add_u64 v[2:3], v[2:3], 0, s[46:47]
	s_add_i32 m0, s7, 0x1e000
	v_bfe_u32 v153, v6, 4, 2
	global_load_lds_dwordx4 v[2:3], off
	s_lshl_b32 s1, s1, 5
	v_and_b32_e32 v152, 15, v6
	v_lshlrev_b32_e32 v2, 4, v153
	v_lshlrev_b32_e32 v3, 2, v6
	s_and_b32 s70, s1, 0x60
	v_lshl_or_b32 v2, v152, 6, v2
	s_lshl_b32 s8, s9, 13
	v_and_b32_e32 v3, 32, v3
	s_lshl_b32 s1, s70, 7
	v_bitop3_b32 v4, v2, s8, v3 bitop3:0xde
	v_bitop3_b32 v154, v2, s1, v3 bitop3:0xde
	v_lshlrev_b32_e32 v2, 14, v8
	s_lshl_b32 s41, s9, 6
	v_and_b32_e32 v2, 0xffff8000, v2
	s_waitcnt vmcnt(6)
	s_cmpk_lt_u32 s0, 0x100
	v_lshl_add_u32 v2, v7, 11, v2
	v_and_b32_e32 v3, 1, v8
	s_cselect_b64 s[48:49], -1, 0
	v_lshl_or_b32 v2, v3, 6, v2
	s_add_i32 s75, 0, 0x10000
	s_add_i32 s76, 0, 0x14000
	s_mov_b32 s71, 0x18000
	s_mov_b32 s72, 0x8000
	s_ashr_i32 s73, s90, 31
	s_mov_b32 s74, s90
	v_lshl_add_u32 v142, v9, 1, v2
	v_mov_b32_e32 v143, v139
	v_mov_b64_e32 v[144:145], 0x100
	v_mov_b64_e32 v[146:147], 0xff
	v_add_u32_e32 v155, s75, v154
	v_add_u32_e32 v156, 0, v4
	v_add_u32_e32 v157, s76, v154
	s_lshl_b32 s20, s70, 1
	s_mov_b32 s77, 0x40000
	s_mov_b32 s78, 0x48000
	s_mov_b32 s79, 0x50000
	s_mov_b32 s80, s21
	s_barrier
	s_branch .LBB0_187

.LBB0_190:
	ds_read_b128 v[130:133], v155
	ds_read_b128 v[134:137], v155 offset:1024
	ds_read_b128 v[148:151], v155 offset:2048
	ds_read_b128 v[158:161], v155 offset:3072
	ds_read_b128 v[194:197], v157
	ds_read_b128 v[198:201], v157 offset:1024
	ds_read_b128 v[202:205], v157 offset:2048
	ds_read_b128 v[206:209], v157 offset:3072
	s_add_u32 s0, s64, 0xfffc0080
	s_addc_u32 s1, s65, -1
	s_cmp_eq_u32 s68, 12
	s_cselect_b32 s1, s11, s1
	s_cselect_b32 s0, s10, s0
	s_cselect_b32 s31, s63, s67
	s_cselect_b32 s30, s62, s66
	v_lshl_add_u64 v[252:253], s[64:65], 0, v[142:143]
	s_add_i32 m0, s7, 0xc000
	ds_read_b128 v[162:165], v156
	ds_read_b128 v[166:169], v156 offset:1024
	ds_read_b128 v[170:173], v156 offset:2048
	ds_read_b128 v[174:177], v156 offset:3072
	ds_read_b128 v[178:181], v156 offset:4096
	ds_read_b128 v[182:185], v156 offset:5120
	ds_read_b128 v[186:189], v156 offset:6144
	ds_read_b128 v[190:193], v156 offset:7168
	global_load_lds_dwordx4 v[252:253], off
	v_lshl_add_u64 v[252:253], v[252:253], 0, s[14:15]
	s_add_i32 m0, s7, 0xe000
	s_nop 0
	global_load_lds_dwordx4 v[252:253], off
	s_waitcnt vmcnt(8)
	s_waitcnt lgkmcnt(0)
	s_barrier
	s_setprio 1
	v_mfma_f32_16x16x32_bf16 v[126:129], v[130:133], v[162:165], v[126:129]
	v_mfma_f32_16x16x32_bf16 v[122:125], v[148:151], v[162:165], v[122:125]
	v_mfma_f32_16x16x32_bf16 v[118:121], v[130:133], v[170:173], v[118:121]
	v_mfma_f32_16x16x32_bf16 v[114:117], v[148:151], v[170:173], v[114:117]
	v_mfma_f32_16x16x32_bf16 v[110:113], v[130:133], v[178:181], v[110:113]
	v_mfma_f32_16x16x32_bf16 v[106:109], v[148:151], v[178:181], v[106:109]
	v_mfma_f32_16x16x32_bf16 v[102:105], v[130:133], v[186:189], v[102:105]
	v_mfma_f32_16x16x32_bf16 v[98:101], v[148:151], v[186:189], v[98:101]
	v_mfma_f32_16x16x32_bf16 v[126:129], v[134:137], v[166:169], v[126:129]
	v_mfma_f32_16x16x32_bf16 v[122:125], v[158:161], v[166:169], v[122:125]
	v_mfma_f32_16x16x32_bf16 v[118:121], v[134:137], v[174:177], v[118:121]
	v_mfma_f32_16x16x32_bf16 v[114:117], v[158:161], v[174:177], v[114:117]
	v_mfma_f32_16x16x32_bf16 v[110:113], v[134:137], v[182:185], v[110:113]
	v_mfma_f32_16x16x32_bf16 v[106:109], v[158:161], v[182:185], v[106:109]
	v_mfma_f32_16x16x32_bf16 v[102:105], v[134:137], v[190:193], v[102:105]
	v_mfma_f32_16x16x32_bf16 v[98:101], v[158:161], v[190:193], v[98:101]
	v_mfma_f32_16x16x32_bf16 v[62:65], v[194:197], v[162:165], v[62:65]
	v_mfma_f32_16x16x32_bf16 v[58:61], v[202:205], v[162:165], v[58:61]
	v_mfma_f32_16x16x32_bf16 v[54:57], v[194:197], v[170:173], v[54:57]
	v_mfma_f32_16x16x32_bf16 v[50:53], v[202:205], v[170:173], v[50:53]
	v_mfma_f32_16x16x32_bf16 v[46:49], v[194:197], v[178:181], v[46:49]
	v_mfma_f32_16x16x32_bf16 v[42:45], v[202:205], v[178:181], v[42:45]
	v_mfma_f32_16x16x32_bf16 v[38:41], v[194:197], v[186:189], v[38:41]
	v_mfma_f32_16x16x32_bf16 v[34:37], v[202:205], v[186:189], v[34:37]
	v_mfma_f32_16x16x32_bf16 v[62:65], v[198:201], v[166:169], v[62:65]
	v_mfma_f32_16x16x32_bf16 v[58:61], v[206:209], v[166:169], v[58:61]
	v_mfma_f32_16x16x32_bf16 v[54:57], v[198:201], v[174:177], v[54:57]
	v_mfma_f32_16x16x32_bf16 v[50:53], v[206:209], v[174:177], v[50:53]
	v_mfma_f32_16x16x32_bf16 v[46:49], v[198:201], v[182:185], v[46:49]
	v_mfma_f32_16x16x32_bf16 v[42:45], v[206:209], v[182:185], v[42:45]
	v_mfma_f32_16x16x32_bf16 v[38:41], v[198:201], v[190:193], v[38:41]
	v_mfma_f32_16x16x32_bf16 v[34:37], v[206:209], v[190:193], v[34:37]
	s_setprio 0
	s_barrier
	ds_read_b128 v[162:165], v156 offset:16384
	ds_read_b128 v[166:169], v156 offset:17408
	ds_read_b128 v[170:173], v156 offset:18432
	ds_read_b128 v[174:177], v156 offset:19456
	ds_read_b128 v[178:181], v156 offset:20480
	ds_read_b128 v[182:185], v156 offset:21504
	ds_read_b128 v[186:189], v156 offset:22528
	ds_read_b128 v[190:193], v156 offset:23552
	v_lshl_add_u64 v[212:213], s[0:1], 0, v[140:141]
	v_lshl_add_u64 v[210:211], s[30:31], 0, v[138:139]
	s_add_i32 s30, s75, s5
	s_mov_b32 m0, s30
	s_nop 0
	global_load_lds_dwordx4 v[210:211], off
	v_lshl_add_u64 v[214:215], v[210:211], 0, s[14:15]
	s_add_i32 m0, s30, 0x2000
	s_nop 0
	global_load_lds_dwordx4 v[214:215], off
	s_add_i32 s0, s76, s5
	v_lshl_add_u64 v[250:251], v[210:211], 0, s[16:17]
	s_mov_b32 m0, s0
	s_nop 0
	global_load_lds_dwordx4 v[250:251], off
	v_lshl_add_u64 v[250:251], v[210:211], 0, s[18:19]
	s_add_i32 m0, s0, 0x2000
	s_nop 0
	global_load_lds_dwordx4 v[250:251], off
	s_mov_b32 m0, s7
	s_nop 0
	global_load_lds_dwordx4 v[212:213], off
	v_lshl_add_u64 v[214:215], v[212:213], 0, s[14:15]
	s_mov_b32 m0, s24
	s_nop 0
	global_load_lds_dwordx4 v[214:215], off
	s_waitcnt vmcnt(8)
	s_waitcnt lgkmcnt(0)
	s_barrier
	s_setprio 1
	v_mfma_f32_16x16x32_bf16 v[94:97], v[130:133], v[162:165], v[94:97]
	v_mfma_f32_16x16x32_bf16 v[90:93], v[148:151], v[162:165], v[90:93]
	v_mfma_f32_16x16x32_bf16 v[86:89], v[130:133], v[170:173], v[86:89]
	v_mfma_f32_16x16x32_bf16 v[82:85], v[148:151], v[170:173], v[82:85]
	v_mfma_f32_16x16x32_bf16 v[78:81], v[130:133], v[178:181], v[78:81]
	v_mfma_f32_16x16x32_bf16 v[74:77], v[148:151], v[178:181], v[74:77]
	v_mfma_f32_16x16x32_bf16 v[70:73], v[130:133], v[186:189], v[70:73]
	v_mfma_f32_16x16x32_bf16 v[66:69], v[148:151], v[186:189], v[66:69]
	v_mfma_f32_16x16x32_bf16 v[94:97], v[134:137], v[166:169], v[94:97]
	v_mfma_f32_16x16x32_bf16 v[90:93], v[158:161], v[166:169], v[90:93]
	v_mfma_f32_16x16x32_bf16 v[86:89], v[134:137], v[174:177], v[86:89]
	v_mfma_f32_16x16x32_bf16 v[82:85], v[158:161], v[174:177], v[82:85]
	v_mfma_f32_16x16x32_bf16 v[78:81], v[134:137], v[182:185], v[78:81]
	v_mfma_f32_16x16x32_bf16 v[74:77], v[158:161], v[182:185], v[74:77]
	v_mfma_f32_16x16x32_bf16 v[70:73], v[134:137], v[190:193], v[70:73]
	v_mfma_f32_16x16x32_bf16 v[66:69], v[158:161], v[190:193], v[66:69]
	v_mfma_f32_16x16x32_bf16 v[30:33], v[194:197], v[162:165], v[30:33]
	v_mfma_f32_16x16x32_bf16 v[26:29], v[202:205], v[162:165], v[26:29]
	v_mfma_f32_16x16x32_bf16 v[22:25], v[194:197], v[170:173], v[22:25]
	v_mfma_f32_16x16x32_bf16 v[18:21], v[202:205], v[170:173], v[18:21]
	v_mfma_f32_16x16x32_bf16 v[14:17], v[194:197], v[178:181], v[14:17]
	v_mfma_f32_16x16x32_bf16 v[10:13], v[202:205], v[178:181], v[10:13]
	v_mfma_f32_16x16x32_bf16 v[6:9], v[194:197], v[186:189], v[6:9]
	v_mfma_f32_16x16x32_bf16 v[2:5], v[202:205], v[186:189], v[2:5]
	v_mfma_f32_16x16x32_bf16 v[30:33], v[198:201], v[166:169], v[30:33]
	v_mfma_f32_16x16x32_bf16 v[26:29], v[206:209], v[166:169], v[26:29]
	v_mfma_f32_16x16x32_bf16 v[22:25], v[198:201], v[174:177], v[22:25]
	v_mfma_f32_16x16x32_bf16 v[18:21], v[206:209], v[174:177], v[18:21]
	v_mfma_f32_16x16x32_bf16 v[14:17], v[198:201], v[182:185], v[14:17]
	v_mfma_f32_16x16x32_bf16 v[10:13], v[206:209], v[182:185], v[10:13]
	v_mfma_f32_16x16x32_bf16 v[6:9], v[198:201], v[190:193], v[6:9]
	v_mfma_f32_16x16x32_bf16 v[2:5], v[206:209], v[190:193], v[2:5]
	s_setprio 0
	s_add_i32 s0, 0, 0x18000
	v_add_u32_e32 v158, s0, v154
	s_barrier
	s_add_i32 s1, 0, 0x1c000
	v_add_u32_e32 v206, s1, v154
	ds_read_b128 v[130:133], v158
	ds_read_b128 v[134:137], v158 offset:1024
	ds_read_b128 v[148:151], v158 offset:2048
	ds_read_b128 v[158:161], v158 offset:3072
	ds_read_b128 v[194:197], v206
	ds_read_b128 v[198:201], v206 offset:1024
	ds_read_b128 v[202:205], v206 offset:2048
	ds_read_b128 v[206:209], v206 offset:3072
	s_mov_b32 m0, s25
	v_lshl_add_u64 v[252:253], v[212:213], 0, s[16:17]
	ds_read_b128 v[162:165], v156 offset:32768
	ds_read_b128 v[166:169], v156 offset:33792
	ds_read_b128 v[170:173], v156 offset:34816
	ds_read_b128 v[174:177], v156 offset:35840
	ds_read_b128 v[178:181], v156 offset:36864
	ds_read_b128 v[182:185], v156 offset:37888
	ds_read_b128 v[186:189], v156 offset:38912
	ds_read_b128 v[190:193], v156 offset:39936
	global_load_lds_dwordx4 v[252:253], off
	v_lshl_add_u64 v[252:253], v[212:213], 0, s[18:19]
	s_mov_b32 m0, s26
	s_nop 0
	global_load_lds_dwordx4 v[252:253], off
	s_waitcnt vmcnt(8)
	s_waitcnt lgkmcnt(0)
	s_barrier
	s_setprio 1
	v_mfma_f32_16x16x32_bf16 v[126:129], v[130:133], v[162:165], v[126:129]
	v_mfma_f32_16x16x32_bf16 v[122:125], v[148:151], v[162:165], v[122:125]
	v_mfma_f32_16x16x32_bf16 v[118:121], v[130:133], v[170:173], v[118:121]
	v_mfma_f32_16x16x32_bf16 v[114:117], v[148:151], v[170:173], v[114:117]
	v_mfma_f32_16x16x32_bf16 v[110:113], v[130:133], v[178:181], v[110:113]
	v_mfma_f32_16x16x32_bf16 v[106:109], v[148:151], v[178:181], v[106:109]
	v_mfma_f32_16x16x32_bf16 v[102:105], v[130:133], v[186:189], v[102:105]
	v_mfma_f32_16x16x32_bf16 v[98:101], v[148:151], v[186:189], v[98:101]
	v_mfma_f32_16x16x32_bf16 v[126:129], v[134:137], v[166:169], v[126:129]
	v_mfma_f32_16x16x32_bf16 v[122:125], v[158:161], v[166:169], v[122:125]
	v_mfma_f32_16x16x32_bf16 v[118:121], v[134:137], v[174:177], v[118:121]
	v_mfma_f32_16x16x32_bf16 v[114:117], v[158:161], v[174:177], v[114:117]
	v_mfma_f32_16x16x32_bf16 v[110:113], v[134:137], v[182:185], v[110:113]
	v_mfma_f32_16x16x32_bf16 v[106:109], v[158:161], v[182:185], v[106:109]
	v_mfma_f32_16x16x32_bf16 v[102:105], v[134:137], v[190:193], v[102:105]
	v_mfma_f32_16x16x32_bf16 v[98:101], v[158:161], v[190:193], v[98:101]
	v_mfma_f32_16x16x32_bf16 v[62:65], v[194:197], v[162:165], v[62:65]
	v_mfma_f32_16x16x32_bf16 v[58:61], v[202:205], v[162:165], v[58:61]
	v_mfma_f32_16x16x32_bf16 v[54:57], v[194:197], v[170:173], v[54:57]
	v_mfma_f32_16x16x32_bf16 v[50:53], v[202:205], v[170:173], v[50:53]
	v_mfma_f32_16x16x32_bf16 v[46:49], v[194:197], v[178:181], v[46:49]
	v_mfma_f32_16x16x32_bf16 v[42:45], v[202:205], v[178:181], v[42:45]
	v_mfma_f32_16x16x32_bf16 v[38:41], v[194:197], v[186:189], v[38:41]
	v_mfma_f32_16x16x32_bf16 v[34:37], v[202:205], v[186:189], v[34:37]
	v_mfma_f32_16x16x32_bf16 v[62:65], v[198:201], v[166:169], v[62:65]
	v_mfma_f32_16x16x32_bf16 v[58:61], v[206:209], v[166:169], v[58:61]
	v_mfma_f32_16x16x32_bf16 v[54:57], v[198:201], v[174:177], v[54:57]
	v_mfma_f32_16x16x32_bf16 v[50:53], v[206:209], v[174:177], v[50:53]
	v_mfma_f32_16x16x32_bf16 v[46:49], v[198:201], v[182:185], v[46:49]
	v_mfma_f32_16x16x32_bf16 v[42:45], v[206:209], v[182:185], v[42:45]
	v_mfma_f32_16x16x32_bf16 v[38:41], v[198:201], v[190:193], v[38:41]
	v_mfma_f32_16x16x32_bf16 v[34:37], v[206:209], v[190:193], v[34:37]
	s_setprio 0
	s_barrier
	ds_read_b128 v[162:165], v156 offset:49152
	ds_read_b128 v[166:169], v156 offset:50176
	ds_read_b128 v[170:173], v156 offset:51200
	ds_read_b128 v[174:177], v156 offset:52224
	ds_read_b128 v[178:181], v156 offset:53248
	ds_read_b128 v[182:185], v156 offset:54272
	ds_read_b128 v[186:189], v156 offset:55296
	ds_read_b128 v[190:193], v156 offset:56320
	s_add_i32 s0, s0, s5
	v_lshl_add_u64 v[214:215], v[210:211], 0, s[38:39]
	s_mov_b32 m0, s0
	s_nop 0
	global_load_lds_dwordx4 v[214:215], off
	v_lshl_add_u64 v[214:215], v[210:211], 0, s[42:43]
	s_add_i32 m0, s0, 0x2000
	s_nop 0
	global_load_lds_dwordx4 v[214:215], off
	s_add_i32 s0, s1, s5
	v_lshl_add_u64 v[250:251], v[210:211], 0, s[44:45]
	s_mov_b32 m0, s0
	s_nop 0
	global_load_lds_dwordx4 v[250:251], off
	v_lshl_add_u64 v[250:251], v[210:211], 0, s[46:47]
	s_add_i32 m0, s0, 0x2000
	s_nop 0
	global_load_lds_dwordx4 v[250:251], off
	s_mov_b32 m0, s37
	v_lshl_add_u64 v[214:215], v[212:213], 0, s[38:39]
	global_load_lds_dwordx4 v[214:215], off
	v_lshl_add_u64 v[212:213], v[212:213], 0, s[42:43]
	s_mov_b32 m0, s40
	s_nop 0
	global_load_lds_dwordx4 v[212:213], off
	s_waitcnt vmcnt(8)
	s_waitcnt lgkmcnt(0)
	s_barrier
	s_setprio 1
	v_mfma_f32_16x16x32_bf16 v[94:97], v[130:133], v[162:165], v[94:97]
	v_mfma_f32_16x16x32_bf16 v[90:93], v[148:151], v[162:165], v[90:93]
	v_mfma_f32_16x16x32_bf16 v[86:89], v[130:133], v[170:173], v[86:89]
	v_mfma_f32_16x16x32_bf16 v[82:85], v[148:151], v[170:173], v[82:85]
	v_mfma_f32_16x16x32_bf16 v[78:81], v[130:133], v[178:181], v[78:81]
	v_mfma_f32_16x16x32_bf16 v[74:77], v[148:151], v[178:181], v[74:77]
	v_mfma_f32_16x16x32_bf16 v[70:73], v[130:133], v[186:189], v[70:73]
	v_mfma_f32_16x16x32_bf16 v[66:69], v[148:151], v[186:189], v[66:69]
	v_mfma_f32_16x16x32_bf16 v[94:97], v[134:137], v[166:169], v[94:97]
	v_mfma_f32_16x16x32_bf16 v[90:93], v[158:161], v[166:169], v[90:93]
	v_mfma_f32_16x16x32_bf16 v[86:89], v[134:137], v[174:177], v[86:89]
	v_mfma_f32_16x16x32_bf16 v[82:85], v[158:161], v[174:177], v[82:85]
	v_mfma_f32_16x16x32_bf16 v[78:81], v[134:137], v[182:185], v[78:81]
	v_mfma_f32_16x16x32_bf16 v[74:77], v[158:161], v[182:185], v[74:77]
	v_mfma_f32_16x16x32_bf16 v[70:73], v[134:137], v[190:193], v[70:73]
	v_mfma_f32_16x16x32_bf16 v[66:69], v[158:161], v[190:193], v[66:69]
	v_mfma_f32_16x16x32_bf16 v[30:33], v[194:197], v[162:165], v[30:33]
	v_mfma_f32_16x16x32_bf16 v[26:29], v[202:205], v[162:165], v[26:29]
	v_mfma_f32_16x16x32_bf16 v[22:25], v[194:197], v[170:173], v[22:25]
	v_mfma_f32_16x16x32_bf16 v[18:21], v[202:205], v[170:173], v[18:21]
	v_mfma_f32_16x16x32_bf16 v[14:17], v[194:197], v[178:181], v[14:17]
	v_mfma_f32_16x16x32_bf16 v[10:13], v[202:205], v[178:181], v[10:13]
	v_mfma_f32_16x16x32_bf16 v[6:9], v[194:197], v[186:189], v[6:9]
	v_mfma_f32_16x16x32_bf16 v[2:5], v[202:205], v[186:189], v[2:5]
	v_mfma_f32_16x16x32_bf16 v[30:33], v[198:201], v[166:169], v[30:33]
	v_mfma_f32_16x16x32_bf16 v[26:29], v[206:209], v[166:169], v[26:29]
	v_mfma_f32_16x16x32_bf16 v[22:25], v[198:201], v[174:177], v[22:25]
	v_mfma_f32_16x16x32_bf16 v[18:21], v[206:209], v[174:177], v[18:21]
	v_mfma_f32_16x16x32_bf16 v[14:17], v[198:201], v[182:185], v[14:17]
	v_mfma_f32_16x16x32_bf16 v[10:13], v[206:209], v[182:185], v[10:13]
	v_mfma_f32_16x16x32_bf16 v[6:9], v[198:201], v[190:193], v[6:9]
	v_mfma_f32_16x16x32_bf16 v[2:5], v[206:209], v[190:193], v[2:5]
	s_setprio 0
	s_add_i32 s68, s68, 2
	s_add_u32 s66, s66, 0x100
	s_addc_u32 s67, s67, 0
	s_add_u32 s64, s64, 0x100
	s_addc_u32 s65, s65, 0
	s_cmp_gt_u32 s68, 13
	s_barrier
	s_cbranch_scc0 .LBB0_190
	s_and_b64 vcc, exec, s[48:49]
	s_cbranch_vccz .LBB0_193
	s_barrier

.LBB0_1043:
	s_add_u32 s27, s10, 0x2e00000
	s_addc_u32 s28, s11, 0
	s_add_u32 s29, s10, 0x4e00000
	s_addc_u32 s33, s11, 0
	s_add_u32 s35, s10, 0x2101000
	s_addc_u32 s39, s11, 0
	s_and_b32 s10, s12, 0xff
	s_cmp_lt_u32 s10, 4
	s_sext_i32_i8 s11, s12
	s_cselect_b32 s10, s28, s33
	s_cselect_b32 s30, s27, s29
	s_lshl_b32 s12, s12, 9
	s_and_b32 s12, s12, 0x600
	s_add_u32 s30, s30, s42
	s_addc_u32 s10, s10, s43
	s_add_u32 s62, s30, s12
	s_addc_u32 s63, s10, 0
	s_lshl_b32 s10, s11, 8
	s_ashr_i32 s11, s10, 31
	s_lshl_b64 s[10:11], s[10:11], 2
	s_add_u32 s60, s35, s10
	s_mov_b64 s[42:43], 0x80
	s_addc_u32 s61, s39, s11
	v_lshl_add_u64 v[10:11], v[2:3], 0, s[42:43]
	s_add_i32 m0, s9, 0x18000
	s_mov_b64 s[44:45], 0x20080
	s_waitcnt vmcnt(2)
	s_barrier
	global_load_lds_dwordx4 v[10:11], off
	v_lshl_add_u64 v[10:11], v[2:3], 0, s[44:45]
	s_add_i32 m0, s9, 0x1a000
	s_add_i32 s72, s9, 0x8000
	global_load_lds_dwordx4 v[10:11], off
	v_lshl_add_u64 v[10:11], v[4:5], 0, s[42:43]
	s_mov_b32 m0, s72
	s_add_i32 s73, s9, 0xa000
	global_load_lds_dwordx4 v[10:11], off
	v_lshl_add_u64 v[4:5], v[4:5], 0, s[44:45]
	s_mov_b32 m0, s73
	s_mov_b64 s[46:47], 0x40080
	global_load_lds_dwordx4 v[4:5], off
	v_lshl_add_u64 v[4:5], v[2:3], 0, s[46:47]
	s_add_i32 m0, s9, 0x1c000
	s_mov_b64 s[48:49], 0x60080
	global_load_lds_dwordx4 v[4:5], off
	v_lshl_add_u64 v[2:3], v[2:3], 0, s[48:49]
	s_add_i32 m0, s9, 0x1e000
	v_bfe_u32 v153, v6, 4, 2
	global_load_lds_dwordx4 v[2:3], off
	s_lshl_b32 s1, s1, 5
	v_and_b32_e32 v152, 15, v6
	v_lshlrev_b32_e32 v2, 4, v153
	v_lshlrev_b32_e32 v3, 2, v6
	s_and_b32 s75, s1, 0x60
	v_lshl_or_b32 v2, v152, 6, v2
	s_lshl_b32 s10, s13, 13
	v_and_b32_e32 v3, 32, v3
	s_lshl_b32 s1, s75, 7
	v_bitop3_b32 v4, v2, s10, v3 bitop3:0xde
	v_bitop3_b32 v154, v2, s1, v3 bitop3:0xde
	v_lshlrev_b32_e32 v2, 14, v8
	s_lshl_b32 s74, s13, 6
	v_and_b32_e32 v2, 0xffff8000, v2
	s_waitcnt vmcnt(6)
	s_cmpk_lt_u32 s0, 0x100
	v_lshl_add_u32 v2, v7, 11, v2
	v_and_b32_e32 v3, 1, v8
	s_cselect_b64 s[50:51], -1, 0
	v_lshl_or_b32 v2, v3, 6, v2
	s_add_i32 s78, 0, 0x10000
	s_add_i32 s79, 0, 0x14000
	s_ashr_i32 s76, s90, 31
	s_mov_b32 s77, s90
	v_lshl_add_u32 v142, v9, 1, v2
	v_mov_b32_e32 v143, v139
	v_mov_b64_e32 v[144:145], 0x200
	v_mov_b64_e32 v[146:147], 0x1ff
	v_add_u32_e32 v155, s78, v154
	v_add_u32_e32 v156, 0, v4
	v_add_u32_e32 v157, s79, v154
	s_lshl_b32 s40, s75, 1
	s_mov_b32 s80, 0x48000
	s_mov_b32 s81, 0x50000
	s_mov_b32 s82, s41
	s_barrier
	s_branch .LBB0_1046

.LBB0_1049:
	ds_read_b128 v[130:133], v155
	ds_read_b128 v[134:137], v155 offset:1024
	ds_read_b128 v[148:151], v155 offset:2048
	ds_read_b128 v[158:161], v155 offset:3072
	ds_read_b128 v[194:197], v157
	ds_read_b128 v[198:201], v157 offset:1024
	ds_read_b128 v[202:205], v157 offset:2048
	ds_read_b128 v[206:209], v157 offset:3072
	s_add_u32 s0, s66, 0xfffc0080
	s_addc_u32 s1, s67, -1
	s_cmp_eq_u32 s69, 12
	s_cselect_b32 s1, s13, s1
	s_cselect_b32 s0, s12, s0
	s_cselect_b32 s31, s65, s68
	s_cselect_b32 s30, s64, s38
	v_lshl_add_u64 v[252:253], s[66:67], 0, v[142:143]
	s_add_i32 m0, s9, 0xc000
	ds_read_b128 v[162:165], v156
	ds_read_b128 v[166:169], v156 offset:1024
	ds_read_b128 v[170:173], v156 offset:2048
	ds_read_b128 v[174:177], v156 offset:3072
	ds_read_b128 v[178:181], v156 offset:4096
	ds_read_b128 v[182:185], v156 offset:5120
	ds_read_b128 v[186:189], v156 offset:6144
	ds_read_b128 v[190:193], v156 offset:7168
	global_load_lds_dwordx4 v[252:253], off
	v_lshl_add_u64 v[252:253], v[252:253], 0, s[14:15]
	s_add_i32 m0, s9, 0xe000
	s_nop 0
	global_load_lds_dwordx4 v[252:253], off
	s_waitcnt vmcnt(8)
	s_waitcnt lgkmcnt(0)
	s_barrier
	s_setprio 1
	v_mfma_f32_16x16x32_bf16 v[126:129], v[130:133], v[162:165], v[126:129]
	v_mfma_f32_16x16x32_bf16 v[122:125], v[148:151], v[162:165], v[122:125]
	v_mfma_f32_16x16x32_bf16 v[118:121], v[130:133], v[170:173], v[118:121]
	v_mfma_f32_16x16x32_bf16 v[114:117], v[148:151], v[170:173], v[114:117]
	v_mfma_f32_16x16x32_bf16 v[110:113], v[130:133], v[178:181], v[110:113]
	v_mfma_f32_16x16x32_bf16 v[106:109], v[148:151], v[178:181], v[106:109]
	v_mfma_f32_16x16x32_bf16 v[102:105], v[130:133], v[186:189], v[102:105]
	v_mfma_f32_16x16x32_bf16 v[98:101], v[148:151], v[186:189], v[98:101]
	v_mfma_f32_16x16x32_bf16 v[126:129], v[134:137], v[166:169], v[126:129]
	v_mfma_f32_16x16x32_bf16 v[122:125], v[158:161], v[166:169], v[122:125]
	v_mfma_f32_16x16x32_bf16 v[118:121], v[134:137], v[174:177], v[118:121]
	v_mfma_f32_16x16x32_bf16 v[114:117], v[158:161], v[174:177], v[114:117]
	v_mfma_f32_16x16x32_bf16 v[110:113], v[134:137], v[182:185], v[110:113]
	v_mfma_f32_16x16x32_bf16 v[106:109], v[158:161], v[182:185], v[106:109]
	v_mfma_f32_16x16x32_bf16 v[102:105], v[134:137], v[190:193], v[102:105]
	v_mfma_f32_16x16x32_bf16 v[98:101], v[158:161], v[190:193], v[98:101]
	v_mfma_f32_16x16x32_bf16 v[62:65], v[194:197], v[162:165], v[62:65]
	v_mfma_f32_16x16x32_bf16 v[58:61], v[202:205], v[162:165], v[58:61]
	v_mfma_f32_16x16x32_bf16 v[54:57], v[194:197], v[170:173], v[54:57]
	v_mfma_f32_16x16x32_bf16 v[50:53], v[202:205], v[170:173], v[50:53]
	v_mfma_f32_16x16x32_bf16 v[46:49], v[194:197], v[178:181], v[46:49]
	v_mfma_f32_16x16x32_bf16 v[42:45], v[202:205], v[178:181], v[42:45]
	v_mfma_f32_16x16x32_bf16 v[38:41], v[194:197], v[186:189], v[38:41]
	v_mfma_f32_16x16x32_bf16 v[34:37], v[202:205], v[186:189], v[34:37]
	v_mfma_f32_16x16x32_bf16 v[62:65], v[198:201], v[166:169], v[62:65]
	v_mfma_f32_16x16x32_bf16 v[58:61], v[206:209], v[166:169], v[58:61]
	v_mfma_f32_16x16x32_bf16 v[54:57], v[198:201], v[174:177], v[54:57]
	v_mfma_f32_16x16x32_bf16 v[50:53], v[206:209], v[174:177], v[50:53]
	v_mfma_f32_16x16x32_bf16 v[46:49], v[198:201], v[182:185], v[46:49]
	v_mfma_f32_16x16x32_bf16 v[42:45], v[206:209], v[182:185], v[42:45]
	v_mfma_f32_16x16x32_bf16 v[38:41], v[198:201], v[190:193], v[38:41]
	v_mfma_f32_16x16x32_bf16 v[34:37], v[206:209], v[190:193], v[34:37]
	s_setprio 0
	s_barrier
	ds_read_b128 v[162:165], v156 offset:16384
	ds_read_b128 v[166:169], v156 offset:17408
	ds_read_b128 v[170:173], v156 offset:18432
	ds_read_b128 v[174:177], v156 offset:19456
	ds_read_b128 v[178:181], v156 offset:20480
	ds_read_b128 v[182:185], v156 offset:21504
	ds_read_b128 v[186:189], v156 offset:22528
	ds_read_b128 v[190:193], v156 offset:23552
	v_lshl_add_u64 v[212:213], s[0:1], 0, v[140:141]
	v_lshl_add_u64 v[210:211], s[30:31], 0, v[138:139]
	s_add_i32 s30, s78, s7
	s_mov_b32 m0, s30
	s_nop 0
	global_load_lds_dwordx4 v[210:211], off
	v_lshl_add_u64 v[214:215], v[210:211], 0, s[14:15]
	s_add_i32 m0, s30, 0x2000
	s_nop 0
	global_load_lds_dwordx4 v[214:215], off
	s_add_i32 s0, s79, s7
	v_lshl_add_u64 v[250:251], v[210:211], 0, s[18:19]
	s_mov_b32 m0, s0
	s_nop 0
	global_load_lds_dwordx4 v[250:251], off
	v_lshl_add_u64 v[250:251], v[210:211], 0, s[20:21]
	s_add_i32 m0, s0, 0x2000
	s_nop 0
	global_load_lds_dwordx4 v[250:251], off
	s_mov_b32 m0, s9
	s_nop 0
	global_load_lds_dwordx4 v[212:213], off
	v_lshl_add_u64 v[214:215], v[212:213], 0, s[14:15]
	s_mov_b32 m0, s24
	s_nop 0
	global_load_lds_dwordx4 v[214:215], off
	s_waitcnt vmcnt(8)
	s_waitcnt lgkmcnt(0)
	s_barrier
	s_setprio 1
	v_mfma_f32_16x16x32_bf16 v[94:97], v[130:133], v[162:165], v[94:97]
	v_mfma_f32_16x16x32_bf16 v[90:93], v[148:151], v[162:165], v[90:93]
	v_mfma_f32_16x16x32_bf16 v[86:89], v[130:133], v[170:173], v[86:89]
	v_mfma_f32_16x16x32_bf16 v[82:85], v[148:151], v[170:173], v[82:85]
	v_mfma_f32_16x16x32_bf16 v[78:81], v[130:133], v[178:181], v[78:81]
	v_mfma_f32_16x16x32_bf16 v[74:77], v[148:151], v[178:181], v[74:77]
	v_mfma_f32_16x16x32_bf16 v[70:73], v[130:133], v[186:189], v[70:73]
	v_mfma_f32_16x16x32_bf16 v[66:69], v[148:151], v[186:189], v[66:69]
	v_mfma_f32_16x16x32_bf16 v[94:97], v[134:137], v[166:169], v[94:97]
	v_mfma_f32_16x16x32_bf16 v[90:93], v[158:161], v[166:169], v[90:93]
	v_mfma_f32_16x16x32_bf16 v[86:89], v[134:137], v[174:177], v[86:89]
	v_mfma_f32_16x16x32_bf16 v[82:85], v[158:161], v[174:177], v[82:85]
	v_mfma_f32_16x16x32_bf16 v[78:81], v[134:137], v[182:185], v[78:81]
	v_mfma_f32_16x16x32_bf16 v[74:77], v[158:161], v[182:185], v[74:77]
	v_mfma_f32_16x16x32_bf16 v[70:73], v[134:137], v[190:193], v[70:73]
	v_mfma_f32_16x16x32_bf16 v[66:69], v[158:161], v[190:193], v[66:69]
	v_mfma_f32_16x16x32_bf16 v[30:33], v[194:197], v[162:165], v[30:33]
	v_mfma_f32_16x16x32_bf16 v[26:29], v[202:205], v[162:165], v[26:29]
	v_mfma_f32_16x16x32_bf16 v[22:25], v[194:197], v[170:173], v[22:25]
	v_mfma_f32_16x16x32_bf16 v[18:21], v[202:205], v[170:173], v[18:21]
	v_mfma_f32_16x16x32_bf16 v[14:17], v[194:197], v[178:181], v[14:17]
	v_mfma_f32_16x16x32_bf16 v[10:13], v[202:205], v[178:181], v[10:13]
	v_mfma_f32_16x16x32_bf16 v[6:9], v[194:197], v[186:189], v[6:9]
	v_mfma_f32_16x16x32_bf16 v[2:5], v[202:205], v[186:189], v[2:5]
	v_mfma_f32_16x16x32_bf16 v[30:33], v[198:201], v[166:169], v[30:33]
	v_mfma_f32_16x16x32_bf16 v[26:29], v[206:209], v[166:169], v[26:29]
	v_mfma_f32_16x16x32_bf16 v[22:25], v[198:201], v[174:177], v[22:25]
	v_mfma_f32_16x16x32_bf16 v[18:21], v[206:209], v[174:177], v[18:21]
	v_mfma_f32_16x16x32_bf16 v[14:17], v[198:201], v[182:185], v[14:17]
	v_mfma_f32_16x16x32_bf16 v[10:13], v[206:209], v[182:185], v[10:13]
	v_mfma_f32_16x16x32_bf16 v[6:9], v[198:201], v[190:193], v[6:9]
	v_mfma_f32_16x16x32_bf16 v[2:5], v[206:209], v[190:193], v[2:5]
	s_setprio 0
	s_add_i32 s0, 0, 0x18000
	v_add_u32_e32 v158, s0, v154
	s_barrier
	s_add_i32 s1, 0, 0x1c000
	v_add_u32_e32 v206, s1, v154
	ds_read_b128 v[130:133], v158
	ds_read_b128 v[134:137], v158 offset:1024
	ds_read_b128 v[148:151], v158 offset:2048
	ds_read_b128 v[158:161], v158 offset:3072
	ds_read_b128 v[194:197], v206
	ds_read_b128 v[198:201], v206 offset:1024
	ds_read_b128 v[202:205], v206 offset:2048
	ds_read_b128 v[206:209], v206 offset:3072
	s_mov_b32 m0, s25
	v_lshl_add_u64 v[252:253], v[212:213], 0, s[18:19]
	ds_read_b128 v[162:165], v156 offset:32768
	ds_read_b128 v[166:169], v156 offset:33792
	ds_read_b128 v[170:173], v156 offset:34816
	ds_read_b128 v[174:177], v156 offset:35840
	ds_read_b128 v[178:181], v156 offset:36864
	ds_read_b128 v[182:185], v156 offset:37888
	ds_read_b128 v[186:189], v156 offset:38912
	ds_read_b128 v[190:193], v156 offset:39936
	global_load_lds_dwordx4 v[252:253], off
	v_lshl_add_u64 v[252:253], v[212:213], 0, s[20:21]
	s_mov_b32 m0, s26
	s_nop 0
	global_load_lds_dwordx4 v[252:253], off
	s_waitcnt vmcnt(8)
	s_waitcnt lgkmcnt(0)
	s_barrier
	s_setprio 1
	v_mfma_f32_16x16x32_bf16 v[126:129], v[130:133], v[162:165], v[126:129]
	v_mfma_f32_16x16x32_bf16 v[122:125], v[148:151], v[162:165], v[122:125]
	v_mfma_f32_16x16x32_bf16 v[118:121], v[130:133], v[170:173], v[118:121]
	v_mfma_f32_16x16x32_bf16 v[114:117], v[148:151], v[170:173], v[114:117]
	v_mfma_f32_16x16x32_bf16 v[110:113], v[130:133], v[178:181], v[110:113]
	v_mfma_f32_16x16x32_bf16 v[106:109], v[148:151], v[178:181], v[106:109]
	v_mfma_f32_16x16x32_bf16 v[102:105], v[130:133], v[186:189], v[102:105]
	v_mfma_f32_16x16x32_bf16 v[98:101], v[148:151], v[186:189], v[98:101]
	v_mfma_f32_16x16x32_bf16 v[126:129], v[134:137], v[166:169], v[126:129]
	v_mfma_f32_16x16x32_bf16 v[122:125], v[158:161], v[166:169], v[122:125]
	v_mfma_f32_16x16x32_bf16 v[118:121], v[134:137], v[174:177], v[118:121]
	v_mfma_f32_16x16x32_bf16 v[114:117], v[158:161], v[174:177], v[114:117]
	v_mfma_f32_16x16x32_bf16 v[110:113], v[134:137], v[182:185], v[110:113]
	v_mfma_f32_16x16x32_bf16 v[106:109], v[158:161], v[182:185], v[106:109]
	v_mfma_f32_16x16x32_bf16 v[102:105], v[134:137], v[190:193], v[102:105]
	v_mfma_f32_16x16x32_bf16 v[98:101], v[158:161], v[190:193], v[98:101]
	v_mfma_f32_16x16x32_bf16 v[62:65], v[194:197], v[162:165], v[62:65]
	v_mfma_f32_16x16x32_bf16 v[58:61], v[202:205], v[162:165], v[58:61]
	v_mfma_f32_16x16x32_bf16 v[54:57], v[194:197], v[170:173], v[54:57]
	v_mfma_f32_16x16x32_bf16 v[50:53], v[202:205], v[170:173], v[50:53]
	v_mfma_f32_16x16x32_bf16 v[46:49], v[194:197], v[178:181], v[46:49]
	v_mfma_f32_16x16x32_bf16 v[42:45], v[202:205], v[178:181], v[42:45]
	v_mfma_f32_16x16x32_bf16 v[38:41], v[194:197], v[186:189], v[38:41]
	v_mfma_f32_16x16x32_bf16 v[34:37], v[202:205], v[186:189], v[34:37]
	v_mfma_f32_16x16x32_bf16 v[62:65], v[198:201], v[166:169], v[62:65]
	v_mfma_f32_16x16x32_bf16 v[58:61], v[206:209], v[166:169], v[58:61]
	v_mfma_f32_16x16x32_bf16 v[54:57], v[198:201], v[174:177], v[54:57]
	v_mfma_f32_16x16x32_bf16 v[50:53], v[206:209], v[174:177], v[50:53]
	v_mfma_f32_16x16x32_bf16 v[46:49], v[198:201], v[182:185], v[46:49]
	v_mfma_f32_16x16x32_bf16 v[42:45], v[206:209], v[182:185], v[42:45]
	v_mfma_f32_16x16x32_bf16 v[38:41], v[198:201], v[190:193], v[38:41]
	v_mfma_f32_16x16x32_bf16 v[34:37], v[206:209], v[190:193], v[34:37]
	s_setprio 0
	s_barrier
	ds_read_b128 v[162:165], v156 offset:49152
	ds_read_b128 v[166:169], v156 offset:50176
	ds_read_b128 v[170:173], v156 offset:51200
	ds_read_b128 v[174:177], v156 offset:52224
	ds_read_b128 v[178:181], v156 offset:53248
	ds_read_b128 v[182:185], v156 offset:54272
	ds_read_b128 v[186:189], v156 offset:55296
	ds_read_b128 v[190:193], v156 offset:56320
	s_add_i32 s0, s0, s7
	v_lshl_add_u64 v[214:215], v[210:211], 0, s[42:43]
	s_mov_b32 m0, s0
	s_nop 0
	global_load_lds_dwordx4 v[214:215], off
	v_lshl_add_u64 v[214:215], v[210:211], 0, s[44:45]
	s_add_i32 m0, s0, 0x2000
	s_nop 0
	global_load_lds_dwordx4 v[214:215], off
	s_add_i32 s0, s1, s7
	v_lshl_add_u64 v[250:251], v[210:211], 0, s[46:47]
	s_mov_b32 m0, s0
	s_nop 0
	global_load_lds_dwordx4 v[250:251], off
	v_lshl_add_u64 v[250:251], v[210:211], 0, s[48:49]
	s_add_i32 m0, s0, 0x2000
	s_nop 0
	global_load_lds_dwordx4 v[250:251], off
	s_mov_b32 m0, s72
	v_lshl_add_u64 v[214:215], v[212:213], 0, s[42:43]
	global_load_lds_dwordx4 v[214:215], off
	v_lshl_add_u64 v[212:213], v[212:213], 0, s[44:45]
	s_mov_b32 m0, s73
	s_nop 0
	global_load_lds_dwordx4 v[212:213], off
	s_waitcnt vmcnt(8)
	s_waitcnt lgkmcnt(0)
	s_barrier
	s_setprio 1
	v_mfma_f32_16x16x32_bf16 v[94:97], v[130:133], v[162:165], v[94:97]
	v_mfma_f32_16x16x32_bf16 v[90:93], v[148:151], v[162:165], v[90:93]
	v_mfma_f32_16x16x32_bf16 v[86:89], v[130:133], v[170:173], v[86:89]
	v_mfma_f32_16x16x32_bf16 v[82:85], v[148:151], v[170:173], v[82:85]
	v_mfma_f32_16x16x32_bf16 v[78:81], v[130:133], v[178:181], v[78:81]
	v_mfma_f32_16x16x32_bf16 v[74:77], v[148:151], v[178:181], v[74:77]
	v_mfma_f32_16x16x32_bf16 v[70:73], v[130:133], v[186:189], v[70:73]
	v_mfma_f32_16x16x32_bf16 v[66:69], v[148:151], v[186:189], v[66:69]
	v_mfma_f32_16x16x32_bf16 v[94:97], v[134:137], v[166:169], v[94:97]
	v_mfma_f32_16x16x32_bf16 v[90:93], v[158:161], v[166:169], v[90:93]
	v_mfma_f32_16x16x32_bf16 v[86:89], v[134:137], v[174:177], v[86:89]
	v_mfma_f32_16x16x32_bf16 v[82:85], v[158:161], v[174:177], v[82:85]
	v_mfma_f32_16x16x32_bf16 v[78:81], v[134:137], v[182:185], v[78:81]
	v_mfma_f32_16x16x32_bf16 v[74:77], v[158:161], v[182:185], v[74:77]
	v_mfma_f32_16x16x32_bf16 v[70:73], v[134:137], v[190:193], v[70:73]
	v_mfma_f32_16x16x32_bf16 v[66:69], v[158:161], v[190:193], v[66:69]
	v_mfma_f32_16x16x32_bf16 v[30:33], v[194:197], v[162:165], v[30:33]
	v_mfma_f32_16x16x32_bf16 v[26:29], v[202:205], v[162:165], v[26:29]
	v_mfma_f32_16x16x32_bf16 v[22:25], v[194:197], v[170:173], v[22:25]
	v_mfma_f32_16x16x32_bf16 v[18:21], v[202:205], v[170:173], v[18:21]
	v_mfma_f32_16x16x32_bf16 v[14:17], v[194:197], v[178:181], v[14:17]
	v_mfma_f32_16x16x32_bf16 v[10:13], v[202:205], v[178:181], v[10:13]
	v_mfma_f32_16x16x32_bf16 v[6:9], v[194:197], v[186:189], v[6:9]
	v_mfma_f32_16x16x32_bf16 v[2:5], v[202:205], v[186:189], v[2:5]
	v_mfma_f32_16x16x32_bf16 v[30:33], v[198:201], v[166:169], v[30:33]
	v_mfma_f32_16x16x32_bf16 v[26:29], v[206:209], v[166:169], v[26:29]
	v_mfma_f32_16x16x32_bf16 v[22:25], v[198:201], v[174:177], v[22:25]
	v_mfma_f32_16x16x32_bf16 v[18:21], v[206:209], v[174:177], v[18:21]
	v_mfma_f32_16x16x32_bf16 v[14:17], v[198:201], v[182:185], v[14:17]
	v_mfma_f32_16x16x32_bf16 v[10:13], v[206:209], v[182:185], v[10:13]
	v_mfma_f32_16x16x32_bf16 v[6:9], v[198:201], v[190:193], v[6:9]
	v_mfma_f32_16x16x32_bf16 v[2:5], v[206:209], v[190:193], v[2:5]
	s_setprio 0
	s_add_i32 s69, s69, 2
	s_add_u32 s38, s38, 0x100
	s_addc_u32 s68, s68, 0
	s_add_u32 s66, s66, 0x100
	s_addc_u32 s67, s67, 0
	s_cmp_gt_u32 s69, 13
	s_barrier
	s_cbranch_scc0 .LBB0_1049
	s_and_b64 vcc, exec, s[50:51]
	s_cbranch_vccz .LBB0_1052
	s_barrier

.LBB0_1625:
	s_add_u32 s27, s10, 0x6e00000
	s_addc_u32 s28, s11, 0
	s_add_u32 s29, s10, 0x8e00000
	s_addc_u32 s33, s11, 0
	s_cmpk_lt_u32 s2, 0x100
	s_cselect_b32 s34, s33, 0
	s_cselect_b32 s35, s29, 0
	s_cmp_eq_u32 s31, 1
	s_cselect_b32 s37, s27, 0
	s_cselect_b32 s36, s28, 0
	s_add_u32 s35, s37, s35
	s_addc_u32 s34, s36, s34
	s_cmp_eq_u32 s31, 2
	s_cselect_b32 s36, s8, 0
	s_cselect_b32 s31, s9, 0
	s_add_u32 s35, s35, s36
	s_addc_u32 s31, s34, s31
	s_or_b32 s23, s23, s30
	s_lshl_b32 s23, s23, 1
	s_add_u32 s52, s35, s23
	s_addc_u32 s53, s31, 0
	s_add_u32 s64, s10, 0x2103000
	s_addc_u32 s65, s11, 0
	s_ashr_i32 s23, s22, 31
	s_lshl_b64 s[22:23], s[22:23], 2
	s_add_u32 s22, s64, s22
	s_addc_u32 s23, s65, s23
	s_lshl_b32 s30, s30, 2
	s_add_u32 s54, s22, s30
	s_addc_u32 s55, s23, 0
	s_mov_b64 s[22:23], 0x80
	v_lshl_add_u64 v[10:11], v[2:3], 0, s[22:23]
	s_add_i32 m0, s6, 0x18000
	s_mov_b64 s[34:35], 0x20080
	s_waitcnt vmcnt(2)
	s_barrier
	global_load_lds_dwordx4 v[10:11], off
	v_lshl_add_u64 v[10:11], v[2:3], 0, s[34:35]
	s_add_i32 m0, s6, 0x1a000
	s_add_i32 s66, s6, 0x8000
	global_load_lds_dwordx4 v[10:11], off
	v_lshl_add_u64 v[10:11], v[4:5], 0, s[22:23]
	s_mov_b32 m0, s66
	s_add_i32 s67, s6, 0xa000
	global_load_lds_dwordx4 v[10:11], off
	v_lshl_add_u64 v[4:5], v[4:5], 0, s[34:35]
	s_mov_b32 m0, s67
	s_mov_b64 s[36:37], 0x40080
	global_load_lds_dwordx4 v[4:5], off
	v_lshl_add_u64 v[4:5], v[2:3], 0, s[36:37]
	s_add_i32 m0, s6, 0x1c000
	s_mov_b64 s[38:39], 0x60080
	global_load_lds_dwordx4 v[4:5], off
	v_lshl_add_u64 v[2:3], v[2:3], 0, s[38:39]
	s_add_i32 m0, s6, 0x1e000
	v_bfe_u32 v187, v6, 4, 2
	global_load_lds_dwordx4 v[2:3], off
	s_lshl_b32 s1, s1, 5
	v_and_b32_e32 v186, 15, v6
	v_lshlrev_b32_e32 v2, 4, v187
	v_lshlrev_b32_e32 v3, 2, v6
	s_and_b32 s69, s1, 0x60
	s_lshl_b32 s68, s18, 6
	v_lshl_or_b32 v2, v186, 6, v2
	s_lshl_b32 s18, s18, 13
	v_and_b32_e32 v3, 32, v3
	s_lshl_b32 s1, s69, 7
	v_bitop3_b32 v4, v2, s18, v3 bitop3:0xde
	v_bitop3_b32 v188, v2, s1, v3 bitop3:0xde
	v_lshlrev_b32_e32 v2, 14, v8
	v_and_b32_e32 v2, 0xffff8000, v2
	s_waitcnt vmcnt(6)
	s_cmpk_lt_u32 s0, 0x100
	v_lshl_add_u32 v2, v7, 11, v2
	v_and_b32_e32 v3, 1, v8
	s_cselect_b64 s[40:41], -1, 0
	v_lshl_or_b32 v2, v3, 6, v2
	s_add_i32 s72, 0, 0x10000
	s_add_i32 s73, 0, 0x14000
	s_mov_b32 s70, 0x18000
	s_mov_b32 s71, 0x8000
	v_lshl_add_u32 v166, v9, 1, v2
	v_mov_b32_e32 v167, v163
	v_add_u32_e32 v189, s72, v188
	v_add_u32_e32 v190, 0, v4
	v_add_u32_e32 v191, s73, v188
	s_lshl_b32 s18, s69, 1
	s_mov_b32 s74, 0x40000
	s_mov_b32 s75, 0x48000
	s_mov_b32 s76, 0x50000
	s_mov_b32 s77, 0x58000
	s_mov_b32 s78, s19
	s_barrier
	s_branch .LBB0_1628

.LBB0_1631:
	ds_read_b128 v[122:125], v189
	ds_read_b128 v[134:137], v189 offset:1024
	ds_read_b128 v[138:141], v189 offset:2048
	ds_read_b128 v[142:145], v189 offset:3072
	ds_read_b128 v[192:195], v191
	ds_read_b128 v[196:199], v191 offset:1024
	ds_read_b128 v[200:203], v191 offset:2048
	ds_read_b128 v[204:207], v191 offset:3072
	s_add_u32 s0, s60, 0xfffc0080
	s_addc_u32 s1, s61, -1
	s_cmp_eq_u32 s79, 12
	s_cselect_b32 s1, s57, s1
	s_cselect_b32 s0, s56, s0
	s_cselect_b32 s31, s59, s63
	s_cselect_b32 s30, s58, s62
	v_lshl_add_u64 v[252:253], s[60:61], 0, v[166:167]
	s_add_i32 m0, s6, 0xc000
	ds_read_b128 v[146:149], v190
	ds_read_b128 v[150:153], v190 offset:1024
	ds_read_b128 v[154:157], v190 offset:2048
	ds_read_b128 v[158:161], v190 offset:3072
	ds_read_b128 v[168:171], v190 offset:4096
	ds_read_b128 v[172:175], v190 offset:5120
	ds_read_b128 v[176:179], v190 offset:6144
	ds_read_b128 v[180:183], v190 offset:7168
	global_load_lds_dwordx4 v[252:253], off
	v_lshl_add_u64 v[252:253], v[252:253], 0, s[12:13]
	s_add_i32 m0, s6, 0xe000
	s_nop 0
	global_load_lds_dwordx4 v[252:253], off
	s_waitcnt vmcnt(8)
	s_waitcnt lgkmcnt(0)
	s_barrier
	s_setprio 1
	v_mfma_f32_16x16x32_bf16 v[130:133], v[122:125], v[146:149], v[130:133]
	v_mfma_f32_16x16x32_bf16 v[126:129], v[138:141], v[146:149], v[126:129]
	v_mfma_f32_16x16x32_bf16 v[118:121], v[122:125], v[154:157], v[118:121]
	v_mfma_f32_16x16x32_bf16 v[114:117], v[138:141], v[154:157], v[114:117]
	v_mfma_f32_16x16x32_bf16 v[110:113], v[122:125], v[168:171], v[110:113]
	v_mfma_f32_16x16x32_bf16 v[106:109], v[138:141], v[168:171], v[106:109]
	v_mfma_f32_16x16x32_bf16 v[102:105], v[122:125], v[176:179], v[102:105]
	v_mfma_f32_16x16x32_bf16 v[98:101], v[138:141], v[176:179], v[98:101]
	v_mfma_f32_16x16x32_bf16 v[130:133], v[134:137], v[150:153], v[130:133]
	v_mfma_f32_16x16x32_bf16 v[126:129], v[142:145], v[150:153], v[126:129]
	v_mfma_f32_16x16x32_bf16 v[118:121], v[134:137], v[158:161], v[118:121]
	v_mfma_f32_16x16x32_bf16 v[114:117], v[142:145], v[158:161], v[114:117]
	v_mfma_f32_16x16x32_bf16 v[110:113], v[134:137], v[172:175], v[110:113]
	v_mfma_f32_16x16x32_bf16 v[106:109], v[142:145], v[172:175], v[106:109]
	v_mfma_f32_16x16x32_bf16 v[102:105], v[134:137], v[180:183], v[102:105]
	v_mfma_f32_16x16x32_bf16 v[98:101], v[142:145], v[180:183], v[98:101]
	v_mfma_f32_16x16x32_bf16 v[62:65], v[192:195], v[146:149], v[62:65]
	v_mfma_f32_16x16x32_bf16 v[58:61], v[200:203], v[146:149], v[58:61]
	v_mfma_f32_16x16x32_bf16 v[54:57], v[192:195], v[154:157], v[54:57]
	v_mfma_f32_16x16x32_bf16 v[50:53], v[200:203], v[154:157], v[50:53]
	v_mfma_f32_16x16x32_bf16 v[46:49], v[192:195], v[168:171], v[46:49]
	v_mfma_f32_16x16x32_bf16 v[42:45], v[200:203], v[168:171], v[42:45]
	v_mfma_f32_16x16x32_bf16 v[38:41], v[192:195], v[176:179], v[38:41]
	v_mfma_f32_16x16x32_bf16 v[34:37], v[200:203], v[176:179], v[34:37]
	v_mfma_f32_16x16x32_bf16 v[62:65], v[196:199], v[150:153], v[62:65]
	v_mfma_f32_16x16x32_bf16 v[58:61], v[204:207], v[150:153], v[58:61]
	v_mfma_f32_16x16x32_bf16 v[54:57], v[196:199], v[158:161], v[54:57]
	v_mfma_f32_16x16x32_bf16 v[50:53], v[204:207], v[158:161], v[50:53]
	v_mfma_f32_16x16x32_bf16 v[46:49], v[196:199], v[172:175], v[46:49]
	v_mfma_f32_16x16x32_bf16 v[42:45], v[204:207], v[172:175], v[42:45]
	v_mfma_f32_16x16x32_bf16 v[38:41], v[196:199], v[180:183], v[38:41]
	v_mfma_f32_16x16x32_bf16 v[34:37], v[204:207], v[180:183], v[34:37]
	s_setprio 0
	s_barrier
	ds_read_b128 v[146:149], v190 offset:16384
	ds_read_b128 v[150:153], v190 offset:17408
	ds_read_b128 v[154:157], v190 offset:18432
	ds_read_b128 v[158:161], v190 offset:19456
	ds_read_b128 v[168:171], v190 offset:20480
	ds_read_b128 v[172:175], v190 offset:21504
	ds_read_b128 v[176:179], v190 offset:22528
	ds_read_b128 v[180:183], v190 offset:23552
	v_lshl_add_u64 v[208:209], s[0:1], 0, v[164:165]
	v_lshl_add_u64 v[184:185], s[30:31], 0, v[162:163]
	s_add_i32 s30, s72, s5
	s_mov_b32 m0, s30
	s_nop 0
	global_load_lds_dwordx4 v[184:185], off
	v_lshl_add_u64 v[210:211], v[184:185], 0, s[12:13]
	s_add_i32 m0, s30, 0x2000
	s_nop 0
	global_load_lds_dwordx4 v[210:211], off
	s_add_i32 s0, s73, s5
	v_lshl_add_u64 v[250:251], v[184:185], 0, s[14:15]
	s_mov_b32 m0, s0
	s_nop 0
	global_load_lds_dwordx4 v[250:251], off
	v_lshl_add_u64 v[250:251], v[184:185], 0, s[16:17]
	s_add_i32 m0, s0, 0x2000
	s_nop 0
	global_load_lds_dwordx4 v[250:251], off
	s_mov_b32 m0, s6
	s_nop 0
	global_load_lds_dwordx4 v[208:209], off
	v_lshl_add_u64 v[210:211], v[208:209], 0, s[12:13]
	s_mov_b32 m0, s7
	s_nop 0
	global_load_lds_dwordx4 v[210:211], off
	s_waitcnt vmcnt(8)
	s_waitcnt lgkmcnt(0)
	s_barrier
	s_setprio 1
	v_mfma_f32_16x16x32_bf16 v[94:97], v[122:125], v[146:149], v[94:97]
	v_mfma_f32_16x16x32_bf16 v[90:93], v[138:141], v[146:149], v[90:93]
	v_mfma_f32_16x16x32_bf16 v[86:89], v[122:125], v[154:157], v[86:89]
	v_mfma_f32_16x16x32_bf16 v[82:85], v[138:141], v[154:157], v[82:85]
	v_mfma_f32_16x16x32_bf16 v[78:81], v[122:125], v[168:171], v[78:81]
	v_mfma_f32_16x16x32_bf16 v[74:77], v[138:141], v[168:171], v[74:77]
	v_mfma_f32_16x16x32_bf16 v[70:73], v[122:125], v[176:179], v[70:73]
	v_mfma_f32_16x16x32_bf16 v[66:69], v[138:141], v[176:179], v[66:69]
	v_mfma_f32_16x16x32_bf16 v[94:97], v[134:137], v[150:153], v[94:97]
	v_mfma_f32_16x16x32_bf16 v[90:93], v[142:145], v[150:153], v[90:93]
	v_mfma_f32_16x16x32_bf16 v[86:89], v[134:137], v[158:161], v[86:89]
	v_mfma_f32_16x16x32_bf16 v[82:85], v[142:145], v[158:161], v[82:85]
	v_mfma_f32_16x16x32_bf16 v[78:81], v[134:137], v[172:175], v[78:81]
	v_mfma_f32_16x16x32_bf16 v[74:77], v[142:145], v[172:175], v[74:77]
	v_mfma_f32_16x16x32_bf16 v[70:73], v[134:137], v[180:183], v[70:73]
	v_mfma_f32_16x16x32_bf16 v[66:69], v[142:145], v[180:183], v[66:69]
	v_mfma_f32_16x16x32_bf16 v[30:33], v[192:195], v[146:149], v[30:33]
	v_mfma_f32_16x16x32_bf16 v[26:29], v[200:203], v[146:149], v[26:29]
	v_mfma_f32_16x16x32_bf16 v[22:25], v[192:195], v[154:157], v[22:25]
	v_mfma_f32_16x16x32_bf16 v[18:21], v[200:203], v[154:157], v[18:21]
	v_mfma_f32_16x16x32_bf16 v[14:17], v[192:195], v[168:171], v[14:17]
	v_mfma_f32_16x16x32_bf16 v[10:13], v[200:203], v[168:171], v[10:13]
	v_mfma_f32_16x16x32_bf16 v[6:9], v[192:195], v[176:179], v[6:9]
	v_mfma_f32_16x16x32_bf16 v[2:5], v[200:203], v[176:179], v[2:5]
	v_mfma_f32_16x16x32_bf16 v[30:33], v[196:199], v[150:153], v[30:33]
	v_mfma_f32_16x16x32_bf16 v[26:29], v[204:207], v[150:153], v[26:29]
	v_mfma_f32_16x16x32_bf16 v[22:25], v[196:199], v[158:161], v[22:25]
	v_mfma_f32_16x16x32_bf16 v[18:21], v[204:207], v[158:161], v[18:21]
	v_mfma_f32_16x16x32_bf16 v[14:17], v[196:199], v[172:175], v[14:17]
	v_mfma_f32_16x16x32_bf16 v[10:13], v[204:207], v[172:175], v[10:13]
	v_mfma_f32_16x16x32_bf16 v[6:9], v[196:199], v[180:183], v[6:9]
	v_mfma_f32_16x16x32_bf16 v[2:5], v[204:207], v[180:183], v[2:5]
	s_setprio 0
	s_add_i32 s0, 0, 0x18000
	v_add_u32_e32 v142, s0, v188
	s_barrier
	s_add_i32 s1, 0, 0x1c000
	v_add_u32_e32 v204, s1, v188
	ds_read_b128 v[122:125], v142
	ds_read_b128 v[134:137], v142 offset:1024
	ds_read_b128 v[138:141], v142 offset:2048
	ds_read_b128 v[142:145], v142 offset:3072
	ds_read_b128 v[192:195], v204
	ds_read_b128 v[196:199], v204 offset:1024
	ds_read_b128 v[200:203], v204 offset:2048
	ds_read_b128 v[204:207], v204 offset:3072
	s_mov_b32 m0, s24
	v_lshl_add_u64 v[252:253], v[208:209], 0, s[14:15]
	ds_read_b128 v[146:149], v190 offset:32768
	ds_read_b128 v[150:153], v190 offset:33792
	ds_read_b128 v[154:157], v190 offset:34816
	ds_read_b128 v[158:161], v190 offset:35840
	ds_read_b128 v[168:171], v190 offset:36864
	ds_read_b128 v[172:175], v190 offset:37888
	ds_read_b128 v[176:179], v190 offset:38912
	ds_read_b128 v[180:183], v190 offset:39936
	global_load_lds_dwordx4 v[252:253], off
	v_lshl_add_u64 v[252:253], v[208:209], 0, s[16:17]
	s_mov_b32 m0, s25
	s_nop 0
	global_load_lds_dwordx4 v[252:253], off
	s_waitcnt vmcnt(8)
	s_waitcnt lgkmcnt(0)
	s_barrier
	s_setprio 1
	v_mfma_f32_16x16x32_bf16 v[130:133], v[122:125], v[146:149], v[130:133]
	v_mfma_f32_16x16x32_bf16 v[126:129], v[138:141], v[146:149], v[126:129]
	v_mfma_f32_16x16x32_bf16 v[118:121], v[122:125], v[154:157], v[118:121]
	v_mfma_f32_16x16x32_bf16 v[114:117], v[138:141], v[154:157], v[114:117]
	v_mfma_f32_16x16x32_bf16 v[110:113], v[122:125], v[168:171], v[110:113]
	v_mfma_f32_16x16x32_bf16 v[106:109], v[138:141], v[168:171], v[106:109]
	v_mfma_f32_16x16x32_bf16 v[102:105], v[122:125], v[176:179], v[102:105]
	v_mfma_f32_16x16x32_bf16 v[98:101], v[138:141], v[176:179], v[98:101]
	v_mfma_f32_16x16x32_bf16 v[130:133], v[134:137], v[150:153], v[130:133]
	v_mfma_f32_16x16x32_bf16 v[126:129], v[142:145], v[150:153], v[126:129]
	v_mfma_f32_16x16x32_bf16 v[118:121], v[134:137], v[158:161], v[118:121]
	v_mfma_f32_16x16x32_bf16 v[114:117], v[142:145], v[158:161], v[114:117]
	v_mfma_f32_16x16x32_bf16 v[110:113], v[134:137], v[172:175], v[110:113]
	v_mfma_f32_16x16x32_bf16 v[106:109], v[142:145], v[172:175], v[106:109]
	v_mfma_f32_16x16x32_bf16 v[102:105], v[134:137], v[180:183], v[102:105]
	v_mfma_f32_16x16x32_bf16 v[98:101], v[142:145], v[180:183], v[98:101]
	v_mfma_f32_16x16x32_bf16 v[62:65], v[192:195], v[146:149], v[62:65]
	v_mfma_f32_16x16x32_bf16 v[58:61], v[200:203], v[146:149], v[58:61]
	v_mfma_f32_16x16x32_bf16 v[54:57], v[192:195], v[154:157], v[54:57]
	v_mfma_f32_16x16x32_bf16 v[50:53], v[200:203], v[154:157], v[50:53]
	v_mfma_f32_16x16x32_bf16 v[46:49], v[192:195], v[168:171], v[46:49]
	v_mfma_f32_16x16x32_bf16 v[42:45], v[200:203], v[168:171], v[42:45]
	v_mfma_f32_16x16x32_bf16 v[38:41], v[192:195], v[176:179], v[38:41]
	v_mfma_f32_16x16x32_bf16 v[34:37], v[200:203], v[176:179], v[34:37]
	v_mfma_f32_16x16x32_bf16 v[62:65], v[196:199], v[150:153], v[62:65]
	v_mfma_f32_16x16x32_bf16 v[58:61], v[204:207], v[150:153], v[58:61]
	v_mfma_f32_16x16x32_bf16 v[54:57], v[196:199], v[158:161], v[54:57]
	v_mfma_f32_16x16x32_bf16 v[50:53], v[204:207], v[158:161], v[50:53]
	v_mfma_f32_16x16x32_bf16 v[46:49], v[196:199], v[172:175], v[46:49]
	v_mfma_f32_16x16x32_bf16 v[42:45], v[204:207], v[172:175], v[42:45]
	v_mfma_f32_16x16x32_bf16 v[38:41], v[196:199], v[180:183], v[38:41]
	v_mfma_f32_16x16x32_bf16 v[34:37], v[204:207], v[180:183], v[34:37]
	s_setprio 0
	s_barrier
	ds_read_b128 v[146:149], v190 offset:49152
	ds_read_b128 v[150:153], v190 offset:50176
	ds_read_b128 v[154:157], v190 offset:51200
	ds_read_b128 v[158:161], v190 offset:52224
	ds_read_b128 v[168:171], v190 offset:53248
	ds_read_b128 v[172:175], v190 offset:54272
	ds_read_b128 v[176:179], v190 offset:55296
	ds_read_b128 v[180:183], v190 offset:56320
	s_add_i32 s0, s0, s5
	v_lshl_add_u64 v[210:211], v[184:185], 0, s[22:23]
	s_mov_b32 m0, s0
	s_nop 0
	global_load_lds_dwordx4 v[210:211], off
	v_lshl_add_u64 v[210:211], v[184:185], 0, s[34:35]
	s_add_i32 m0, s0, 0x2000
	s_nop 0
	global_load_lds_dwordx4 v[210:211], off
	s_add_i32 s0, s1, s5
	v_lshl_add_u64 v[250:251], v[184:185], 0, s[36:37]
	s_mov_b32 m0, s0
	s_nop 0
	global_load_lds_dwordx4 v[250:251], off
	v_lshl_add_u64 v[250:251], v[184:185], 0, s[38:39]
	s_add_i32 m0, s0, 0x2000
	s_nop 0
	global_load_lds_dwordx4 v[250:251], off
	s_mov_b32 m0, s66
	v_lshl_add_u64 v[210:211], v[208:209], 0, s[22:23]
	global_load_lds_dwordx4 v[210:211], off
	v_lshl_add_u64 v[208:209], v[208:209], 0, s[34:35]
	s_mov_b32 m0, s67
	s_nop 0
	global_load_lds_dwordx4 v[208:209], off
	s_waitcnt vmcnt(8)
	s_waitcnt lgkmcnt(0)
	s_barrier
	s_setprio 1
	v_mfma_f32_16x16x32_bf16 v[94:97], v[122:125], v[146:149], v[94:97]
	v_mfma_f32_16x16x32_bf16 v[90:93], v[138:141], v[146:149], v[90:93]
	v_mfma_f32_16x16x32_bf16 v[86:89], v[122:125], v[154:157], v[86:89]
	v_mfma_f32_16x16x32_bf16 v[82:85], v[138:141], v[154:157], v[82:85]
	v_mfma_f32_16x16x32_bf16 v[78:81], v[122:125], v[168:171], v[78:81]
	v_mfma_f32_16x16x32_bf16 v[74:77], v[138:141], v[168:171], v[74:77]
	v_mfma_f32_16x16x32_bf16 v[70:73], v[122:125], v[176:179], v[70:73]
	v_mfma_f32_16x16x32_bf16 v[66:69], v[138:141], v[176:179], v[66:69]
	v_mfma_f32_16x16x32_bf16 v[94:97], v[134:137], v[150:153], v[94:97]
	v_mfma_f32_16x16x32_bf16 v[90:93], v[142:145], v[150:153], v[90:93]
	v_mfma_f32_16x16x32_bf16 v[86:89], v[134:137], v[158:161], v[86:89]
	v_mfma_f32_16x16x32_bf16 v[82:85], v[142:145], v[158:161], v[82:85]
	v_mfma_f32_16x16x32_bf16 v[78:81], v[134:137], v[172:175], v[78:81]
	v_mfma_f32_16x16x32_bf16 v[74:77], v[142:145], v[172:175], v[74:77]
	v_mfma_f32_16x16x32_bf16 v[70:73], v[134:137], v[180:183], v[70:73]
	v_mfma_f32_16x16x32_bf16 v[66:69], v[142:145], v[180:183], v[66:69]
	v_mfma_f32_16x16x32_bf16 v[30:33], v[192:195], v[146:149], v[30:33]
	v_mfma_f32_16x16x32_bf16 v[26:29], v[200:203], v[146:149], v[26:29]
	v_mfma_f32_16x16x32_bf16 v[22:25], v[192:195], v[154:157], v[22:25]
	v_mfma_f32_16x16x32_bf16 v[18:21], v[200:203], v[154:157], v[18:21]
	v_mfma_f32_16x16x32_bf16 v[14:17], v[192:195], v[168:171], v[14:17]
	v_mfma_f32_16x16x32_bf16 v[10:13], v[200:203], v[168:171], v[10:13]
	v_mfma_f32_16x16x32_bf16 v[6:9], v[192:195], v[176:179], v[6:9]
	v_mfma_f32_16x16x32_bf16 v[2:5], v[200:203], v[176:179], v[2:5]
	v_mfma_f32_16x16x32_bf16 v[30:33], v[196:199], v[150:153], v[30:33]
	v_mfma_f32_16x16x32_bf16 v[26:29], v[204:207], v[150:153], v[26:29]
	v_mfma_f32_16x16x32_bf16 v[22:25], v[196:199], v[158:161], v[22:25]
	v_mfma_f32_16x16x32_bf16 v[18:21], v[204:207], v[158:161], v[18:21]
	v_mfma_f32_16x16x32_bf16 v[14:17], v[196:199], v[172:175], v[14:17]
	v_mfma_f32_16x16x32_bf16 v[10:13], v[204:207], v[172:175], v[10:13]
	v_mfma_f32_16x16x32_bf16 v[6:9], v[196:199], v[180:183], v[6:9]
	v_mfma_f32_16x16x32_bf16 v[2:5], v[204:207], v[180:183], v[2:5]
	s_setprio 0
	s_add_i32 s79, s79, 2
	s_add_u32 s62, s62, 0x100
	s_addc_u32 s63, s63, 0
	s_add_u32 s60, s60, 0x100
	s_addc_u32 s61, s61, 0
	s_cmp_gt_u32 s79, 13
	s_barrier
	s_cbranch_scc0 .LBB0_1631
	s_and_b64 vcc, exec, s[40:41]
	s_cbranch_vccz .LBB0_1634
	s_barrier
